# grid barrier: non-leader workgroups issue the agent-scope L1 invalidate right after arriving (before the release spin) so its completion overlaps the wait
# speedup vs baseline: 1.0002x; 1.0002x over previous
; __device__ __forceinline__ unsigned xb_ld(unsigned* p)              { return __hip_atomic_load(p, __ATOMIC_RELAXED, __HIP_MEMORY_SCOPE_AGENT); }
; __device__ __forceinline__ unsigned xb_add(unsigned* p, unsigned v) { return __hip_atomic_fetch_add(p, v, __ATOMIC_RELAXED, __HIP_MEMORY_SCOPE_AGENT); }
; #define XB_SPIN(cond, bar) do { unsigned _sp = 0; while (cond) { __builtin_amdgcn_s_sleep(1); \
;     if ((++_sp & 255u) == 0u) { if (xb_ld(&(bar)[XB_TMO])) break; if (_sp > XB_SPIN_CAP) { atomicAdd(&(bar)[XB_TMO], 1u); break; } } } } while (0)
; __device__ __forceinline__ void xcd_barrier(const XcdBarrier& b) {
;     ...
;         unsigned nloc = b.st[0], nx = b.st[1];
;         if (nloc == 0u) { xcd_barrier_complete(bar, b.x, nloc, nx); b.st[0] = nloc; b.st[1] = nx; }
;         const unsigned old = xb_add(&bar[XB_XSUB(b.x)], 1u);
;         const unsigned gen = old / nloc;
;         if (old + 1u == (gen + 1u) * nloc) {
;             __builtin_amdgcn_fence(__ATOMIC_RELEASE, "agent");
;             asm volatile("s_waitcnt vmcnt(0)" ::: "memory");
;             const unsigned og = xb_add(&bar[XB_TOP], 1u);
;             const unsigned tg = og / nx;
;             if (og + 1u == (tg + 1u) * nx) xb_add(&bar[XB_TOPGEN], 1u);
;             else XB_SPIN(xb_ld(&bar[XB_TOPGEN]) == tg, bar);
;             __builtin_amdgcn_fence(__ATOMIC_ACQUIRE, "agent");
;             xb_add(&bar[XB_XGEN(b.x)], 1u);
;             asm volatile("s_waitcnt vmcnt(0)" ::: "memory");
;         } else {
;             XB_SPIN(xb_ld(&bar[XB_XGEN(b.x)]) == gen, bar);
.LBB0_274:
	s_or_b64 exec, exec, s[2:3]
	v_cvt_f32_u32_e32 v5, v3
	s_waitcnt vmcnt(0)
	v_readfirstlane_b32 s2, v4
	v_sub_u32_e32 v4, 0, v3
	v_rcp_iflag_f32_e32 v5, v5
	v_add_u32_e32 v6, s2, v0
	v_mul_f32_e32 v5, 0x4f7ffffe, v5
	v_cvt_u32_f32_e32 v5, v5
	v_mul_lo_u32 v0, v4, v5
	v_mul_hi_u32 v0, v5, v0
	v_add_u32_e32 v0, v5, v0
	v_mul_hi_u32 v0, v6, v0
	v_mul_lo_u32 v4, v0, v3
	v_sub_u32_e32 v4, v6, v4
	v_add_u32_e32 v5, 1, v0
	v_cmp_ge_u32_e32 vcc, v4, v3
	s_nop 1
	v_cndmask_b32_e32 v0, v0, v5, vcc
	v_sub_u32_e32 v5, v4, v3
	v_cndmask_b32_e32 v4, v4, v5, vcc
	v_add_u32_e32 v5, 1, v0
	v_cmp_ge_u32_e32 vcc, v4, v3
	v_add_u32_e32 v4, 1, v6
	s_nop 0
	v_cndmask_b32_e32 v0, v0, v5, vcc
	v_mul_lo_u32 v5, v3, v0
	v_add_u32_e32 v3, v5, v3
	v_cmp_ne_u32_e32 vcc, v4, v3
	s_and_saveexec_b64 s[2:3], vcc
	s_xor_b64 s[2:3], exec, s[2:3]
	s_cbranch_execz .LBB0_288
	v_readlane_b32 s4, v255, 9
	v_readlane_b32 s5, v255, 10
	s_waitcnt lgkmcnt(0)
	buffer_inv sc1
	s_nop 3
	global_load_dword v2, v1, s[4:5] sc1
	s_waitcnt vmcnt(0)
	v_cmp_eq_u32_e32 vcc, v2, v0
	s_and_saveexec_b64 s[16:17], vcc
	s_cbranch_execz .LBB0_287
	s_mov_b32 s4, 1
	s_mov_b64 s[18:19], 0
	s_branch .LBB0_278

; __device__ __forceinline__ unsigned xb_ld(unsigned* p)              { return __hip_atomic_load(p, __ATOMIC_RELAXED, __HIP_MEMORY_SCOPE_AGENT); }
; __device__ __forceinline__ unsigned xb_add(unsigned* p, unsigned v) { return __hip_atomic_fetch_add(p, v, __ATOMIC_RELAXED, __HIP_MEMORY_SCOPE_AGENT); }
; #define XB_SPIN(cond, bar) do { unsigned _sp = 0; while (cond) { __builtin_amdgcn_s_sleep(1); \
;     if ((++_sp & 255u) == 0u) { if (xb_ld(&(bar)[XB_TMO])) break; if (_sp > XB_SPIN_CAP) { atomicAdd(&(bar)[XB_TMO], 1u); break; } } } } while (0)
; __device__ __forceinline__ void xcd_barrier(const XcdBarrier& b) {
;     ...
;         const unsigned old = xb_add(&bar[XB_XSUB(b.x)], 1u);
;         const unsigned gen = old / nloc;
;         if (old + 1u == (gen + 1u) * nloc) {
;             __builtin_amdgcn_fence(__ATOMIC_RELEASE, "agent");
;             asm volatile("s_waitcnt vmcnt(0)" ::: "memory");
;             const unsigned og = xb_add(&bar[XB_TOP], 1u);
;             const unsigned tg = og / nx;
;             if (og + 1u == (tg + 1u) * nx) xb_add(&bar[XB_TOPGEN], 1u);
;             else XB_SPIN(xb_ld(&bar[XB_TOPGEN]) == tg, bar);
;             __builtin_amdgcn_fence(__ATOMIC_ACQUIRE, "agent");
;             xb_add(&bar[XB_XGEN(b.x)], 1u);
;             asm volatile("s_waitcnt vmcnt(0)" ::: "memory");
;         } else {
;             XB_SPIN(xb_ld(&bar[XB_XGEN(b.x)]) == gen, bar);
;             __builtin_amdgcn_fence(__ATOMIC_ACQUIRE, "agent");
;             asm volatile("s_waitcnt vmcnt(0)" ::: "memory");
.LBB0_287:
	s_or_b64 exec, exec, s[16:17]
	s_waitcnt vmcnt(0)
.LBB0_288:
	s_andn2_saveexec_b64 s[2:3], s[2:3]
	s_cbranch_execz .LBB0_308
	s_mov_b64 s[2:3], exec
	buffer_wbl2 sc1
	s_waitcnt lgkmcnt(0)
	s_waitcnt vmcnt(0)
	v_mbcnt_lo_u32_b32 v0, s2, 0
	v_mbcnt_hi_u32_b32 v0, s3, v0
	v_cmp_eq_u32_e32 vcc, 0, v0
	s_and_saveexec_b64 s[16:17], vcc
	s_cbranch_execz .LBB0_291
	s_bcnt1_i32_b64 s2, s[2:3]
	v_mov_b32_e32 v3, s2
	v_readlane_b32 s2, v255, 11
	v_readlane_b32 s3, v255, 12
	s_nop 4
	global_atomic_add v3, v1, v3, s[2:3] sc0
